# filter LDS-fill sequence: LDS-write completion waits dropped (only load counts waited)
# baseline (speedup 1.0000x reference)
; #define LAS __attribute__((address_space(3)))
; __device__ __forceinline__ float block_sum(float v, LAS float* RED, int tid) {
;     v = wave_sum(v); __syncthreads(); if ((tid & 63) == 0) RED[tid >> 6] = v; __syncthreads();
;     float s = 0.f;
; #pragma unroll
;     for (int w = 0; w < 8; ++w) s += RED[w];
;     return s;
; __global__ void __launch_bounds__(NTHR, 2) fwd_mega(Args a) {
;     ...
;                     s = block_sum(s, RED, tid); const float inv = 1.0f / (s + EPSF);
;                     for (int i = tid; i < 8192; i += NTHR) { X[PX(i)] = mk2(hf[i] * inv, 0.f); X[PX(8192 + i)] = (i == 0) ? mk2(0.f, 0.f) : mk2(hb[8192 - i] * inv, 0.f); }
.LBB0_513:
	s_or_b64 exec, exec, s[6:7]
	v_add_f32_dpp v1, v1, v1 quad_perm:[1,0,3,2] row_mask:0xf bank_mask:0xf bound_ctrl:1
	s_xor_b64 s[36:37], s[46:47], -1
	s_nop 0
	v_add_f32_dpp v1, v1, v1 quad_perm:[2,3,0,1] row_mask:0xf bank_mask:0xf bound_ctrl:1
	s_barrier
	s_nop 0
	v_add_f32_dpp v1, v1, v1 row_half_mirror row_mask:0xf bank_mask:0xf bound_ctrl:1
	s_nop 1
	v_add_f32_dpp v1, v1, v1 row_mirror row_mask:0xf bank_mask:0xf bound_ctrl:1
	v_mov_b32_e32 v4, v1
	s_nop 1
	v_permlane16_swap_b32_e32 v1, v4
	v_add_f32_e32 v1, v1, v4
	v_mov_b32_e32 v4, v1
	s_nop 1
	v_permlane32_swap_b32_e32 v1, v4
	s_and_saveexec_b64 s[6:7], s[40:41]
	v_add_f32_e32 v1, v1, v4
	v_add_u32_e32 v4, 0, v154
	v_add_u32_e32 v4, 0x21000, v4
	ds_write_b32 v4, v1
	s_or_b64 exec, exec, s[6:7]
	s_waitcnt lgkmcnt(0)
	s_barrier
	s_and_saveexec_b64 s[6:7], s[38:39]
	s_cbranch_execz .LBB0_520
	s_add_i32 s10, 0, 0x21000
	v_mov_b32_e32 v1, s10
	ds_read_b128 v[4:7], v1
	s_mov_b32 s49, s64
	s_waitcnt lgkmcnt(0)
	v_add_f32_e32 v1, 0, v4
	v_add_f32_e32 v1, v1, v5
	v_add_f32_e32 v1, v1, v6
	v_mov_b32_e32 v4, s56
	v_add_f32_e32 v1, v1, v7
	ds_read_b128 v[4:7], v4
	s_waitcnt lgkmcnt(0)
	v_add_f32_e32 v1, v1, v4
	v_add_f32_e32 v1, v1, v5
	v_add_f32_e32 v1, v1, v6
	v_add_f32_e32 v1, v1, v7
	v_add_f32_e32 v1, 0x358637bd, v1
	v_div_scale_f32 v4, s[10:11], v1, v1, 1.0
	v_rcp_f32_e32 v5, v4
	s_lshl_b32 s10, s48, 8
	s_bitset1_b32 s10, 9
	s_add_u32 s10, s10, s14
	v_fma_f32 v6, -v4, v5, 1.0
	v_fmac_f32_e32 v5, v6, v5
	v_div_scale_f32 v6, vcc, 1.0, v1, 1.0
	s_addc_u32 s11, 0, s15
	v_mul_f32_e32 v7, v6, v5
	s_lshl_b64 s[10:11], s[10:11], 15
	v_fma_f32 v8, -v4, v7, v6
	s_add_u32 s4, s4, s10
	v_fmac_f32_e32 v7, v8, v5
	s_addc_u32 s5, s5, s11
	v_fma_f32 v4, -v4, v7, v6
	s_add_u32 s4, s4, 0x1e00000
	v_div_fmas_f32 v4, v4, v5, v7
	s_addc_u32 s5, s5, 0
	s_lshl_b64 s[10:11], s[48:49], 23
	v_div_fixup_f32 v1, v4, v1, 1.0
	v_lshl_add_u64 v[2:3], v[2:3], 0, s[10:11]
	s_mov_b64 s[10:11], 0
	v_mov_b32_e32 v6, v163
	v_mov_b32_e32 v4, v162
	v_mov_b32_e32 v7, v16
	s_mov_b32 s23, 0x10000
	v_mov_b32_e32 v5, v209
	v_lshl_add_u64 v[8:9], v[4:5], 2, s[4:5]
	global_load_dword v10, v[2:3], off
	global_load_dword v13, v[8:9], off
	v_lshl_add_u64 v[2:3], v[2:3], 0, s[16:17]
	global_load_dword v11, v[2:3], off
	global_load_dword v14, v[8:9], off offset:-2048
	v_lshl_add_u64 v[2:3], v[2:3], 0, s[16:17]
	global_load_dword v12, v[2:3], off
	global_load_dword v15, v[8:9], off offset:-4096
	v_lshl_add_u64 v[2:3], v[2:3], 0, s[16:17]
	v_add_u32_e32 v4, -1536, v4
	v_cmp_ne_u32_e32 vcc, 0, v7
	v_ashrrev_i32_e32 v8, 6, v7
	v_lshl_add_u32 v8, v8, 3, v6
	s_waitcnt vmcnt(5) lgkmcnt(0)
	v_mul_f32_e32 v208, v1, v10
	ds_write_b64 v8, v[208:209]
	v_add_u32_e32 v5, 0x2000, v7
	v_ashrrev_i32_e32 v5, 6, v5
	v_lshlrev_b32_e32 v5, 3, v5
	v_add3_u32 v5, v6, v5, s23
	s_waitcnt vmcnt(4)
	v_mul_f32_e32 v208, v1, v13
	v_cndmask_b32_e32 v208, 0, v208, vcc
	ds_write_b64 v5, v[208:209]
	v_add_u32_e32 v6, 0x1000, v6
	v_add_u32_e32 v7, 0x200, v7
	v_cmp_ne_u32_e32 vcc, 0, v7
	v_ashrrev_i32_e32 v8, 6, v7
	v_lshl_add_u32 v8, v8, 3, v6
	s_waitcnt vmcnt(3)
	v_mul_f32_e32 v208, v1, v11
	ds_write_b64 v8, v[208:209]
	v_add_u32_e32 v5, 0x2000, v7
	v_ashrrev_i32_e32 v5, 6, v5
	v_lshlrev_b32_e32 v5, 3, v5
	v_add3_u32 v5, v6, v5, s23
	s_waitcnt vmcnt(2)
	v_mul_f32_e32 v208, v1, v14
	v_cndmask_b32_e32 v208, 0, v208, vcc
	ds_write_b64 v5, v[208:209]
	v_add_u32_e32 v6, 0x1000, v6
	v_add_u32_e32 v7, 0x200, v7
	v_cmp_ne_u32_e32 vcc, 0, v7
	v_ashrrev_i32_e32 v8, 6, v7
	v_lshl_add_u32 v8, v8, 3, v6
	s_waitcnt vmcnt(1)
	v_mul_f32_e32 v208, v1, v12
	ds_write_b64 v8, v[208:209]
	v_add_u32_e32 v5, 0x2000, v7
	v_ashrrev_i32_e32 v5, 6, v5
	v_lshlrev_b32_e32 v5, 3, v5
	v_add3_u32 v5, v6, v5, s23
	s_waitcnt vmcnt(0)
	v_mul_f32_e32 v208, v1, v15
	v_cndmask_b32_e32 v208, 0, v208, vcc
	ds_write_b64 v5, v[208:209]
	v_add_u32_e32 v6, 0x1000, v6
	v_add_u32_e32 v7, 0x200, v7
	v_mov_b32_e32 v5, v209
	v_lshl_add_u64 v[8:9], v[4:5], 2, s[4:5]
	global_load_dword v10, v[2:3], off
	global_load_dword v13, v[8:9], off
	v_lshl_add_u64 v[2:3], v[2:3], 0, s[16:17]
	global_load_dword v11, v[2:3], off
	global_load_dword v14, v[8:9], off offset:-2048
	v_lshl_add_u64 v[2:3], v[2:3], 0, s[16:17]
	global_load_dword v12, v[2:3], off
	global_load_dword v15, v[8:9], off offset:-4096
	v_lshl_add_u64 v[2:3], v[2:3], 0, s[16:17]
	v_add_u32_e32 v4, -1536, v4
	v_cmp_ne_u32_e32 vcc, 0, v7
	v_ashrrev_i32_e32 v8, 6, v7
	v_lshl_add_u32 v8, v8, 3, v6
	s_waitcnt vmcnt(5)
	v_mul_f32_e32 v208, v1, v10
	ds_write_b64 v8, v[208:209]
	v_add_u32_e32 v5, 0x2000, v7
	v_ashrrev_i32_e32 v5, 6, v5
	v_lshlrev_b32_e32 v5, 3, v5
	v_add3_u32 v5, v6, v5, s23
	s_waitcnt vmcnt(4)
	v_mul_f32_e32 v208, v1, v13
	v_cndmask_b32_e32 v208, 0, v208, vcc
	ds_write_b64 v5, v[208:209]
	v_add_u32_e32 v6, 0x1000, v6
	v_add_u32_e32 v7, 0x200, v7
	v_cmp_ne_u32_e32 vcc, 0, v7
	v_ashrrev_i32_e32 v8, 6, v7
	v_lshl_add_u32 v8, v8, 3, v6
	s_waitcnt vmcnt(3)
	v_mul_f32_e32 v208, v1, v11
	ds_write_b64 v8, v[208:209]
	v_add_u32_e32 v5, 0x2000, v7
	v_ashrrev_i32_e32 v5, 6, v5
	v_lshlrev_b32_e32 v5, 3, v5
	v_add3_u32 v5, v6, v5, s23
	s_waitcnt vmcnt(2)
	v_mul_f32_e32 v208, v1, v14
	v_cndmask_b32_e32 v208, 0, v208, vcc
	ds_write_b64 v5, v[208:209]
	v_add_u32_e32 v6, 0x1000, v6
	v_add_u32_e32 v7, 0x200, v7
	v_cmp_ne_u32_e32 vcc, 0, v7
	v_ashrrev_i32_e32 v8, 6, v7
	v_lshl_add_u32 v8, v8, 3, v6
	s_waitcnt vmcnt(1)
	v_mul_f32_e32 v208, v1, v12
	ds_write_b64 v8, v[208:209]
	v_add_u32_e32 v5, 0x2000, v7
	v_ashrrev_i32_e32 v5, 6, v5
	v_lshlrev_b32_e32 v5, 3, v5
	v_add3_u32 v5, v6, v5, s23
	s_waitcnt vmcnt(0)
; __global__ void __launch_bounds__(NTHR, 2) fwd_mega(Args a) {
;     ...
;                     for (int i = tid; i < 8192; i += NTHR) { X[PX(i)] = mk2(hf[i] * inv, 0.f); X[PX(8192 + i)] = (i == 0) ? mk2(0.f, 0.f) : mk2(hb[8192 - i] * inv, 0.f); }
	v_mul_f32_e32 v208, v1, v15
	v_cndmask_b32_e32 v208, 0, v208, vcc
	ds_write_b64 v5, v[208:209]
	v_add_u32_e32 v6, 0x1000, v6
	v_add_u32_e32 v7, 0x200, v7
	v_mov_b32_e32 v5, v209
	v_lshl_add_u64 v[8:9], v[4:5], 2, s[4:5]
	global_load_dword v10, v[2:3], off
	global_load_dword v13, v[8:9], off
	v_lshl_add_u64 v[2:3], v[2:3], 0, s[16:17]
	global_load_dword v11, v[2:3], off
	global_load_dword v14, v[8:9], off offset:-2048
	v_lshl_add_u64 v[2:3], v[2:3], 0, s[16:17]
	global_load_dword v12, v[2:3], off
	global_load_dword v15, v[8:9], off offset:-4096
	v_lshl_add_u64 v[2:3], v[2:3], 0, s[16:17]
	v_add_u32_e32 v4, -1536, v4
	v_cmp_ne_u32_e32 vcc, 0, v7
	v_ashrrev_i32_e32 v8, 6, v7
	v_lshl_add_u32 v8, v8, 3, v6
	s_waitcnt vmcnt(5)
	v_mul_f32_e32 v208, v1, v10
	ds_write_b64 v8, v[208:209]
	v_add_u32_e32 v5, 0x2000, v7
	v_ashrrev_i32_e32 v5, 6, v5
	v_lshlrev_b32_e32 v5, 3, v5
	v_add3_u32 v5, v6, v5, s23
	s_waitcnt vmcnt(4)
	v_mul_f32_e32 v208, v1, v13
	v_cndmask_b32_e32 v208, 0, v208, vcc
	ds_write_b64 v5, v[208:209]
	v_add_u32_e32 v6, 0x1000, v6
	v_add_u32_e32 v7, 0x200, v7
	v_cmp_ne_u32_e32 vcc, 0, v7
	v_ashrrev_i32_e32 v8, 6, v7
	v_lshl_add_u32 v8, v8, 3, v6
	s_waitcnt vmcnt(3)
	v_mul_f32_e32 v208, v1, v11
	ds_write_b64 v8, v[208:209]
	v_add_u32_e32 v5, 0x2000, v7
	v_ashrrev_i32_e32 v5, 6, v5
	v_lshlrev_b32_e32 v5, 3, v5
	v_add3_u32 v5, v6, v5, s23
	s_waitcnt vmcnt(2)
	v_mul_f32_e32 v208, v1, v14
	v_cndmask_b32_e32 v208, 0, v208, vcc
	ds_write_b64 v5, v[208:209]
	v_add_u32_e32 v6, 0x1000, v6
	v_add_u32_e32 v7, 0x200, v7
	v_cmp_ne_u32_e32 vcc, 0, v7
	v_ashrrev_i32_e32 v8, 6, v7
	v_lshl_add_u32 v8, v8, 3, v6
	s_waitcnt vmcnt(1)
	v_mul_f32_e32 v208, v1, v12
	ds_write_b64 v8, v[208:209]
	v_add_u32_e32 v5, 0x2000, v7
	v_ashrrev_i32_e32 v5, 6, v5
	v_lshlrev_b32_e32 v5, 3, v5
	v_add3_u32 v5, v6, v5, s23
	s_waitcnt vmcnt(0)
	v_mul_f32_e32 v208, v1, v15
	v_cndmask_b32_e32 v208, 0, v208, vcc
	ds_write_b64 v5, v[208:209]
	v_add_u32_e32 v6, 0x1000, v6
	v_add_u32_e32 v7, 0x200, v7
	v_mov_b32_e32 v5, v209
	v_lshl_add_u64 v[8:9], v[4:5], 2, s[4:5]
	global_load_dword v10, v[2:3], off
	global_load_dword v13, v[8:9], off
	v_lshl_add_u64 v[2:3], v[2:3], 0, s[16:17]
	global_load_dword v11, v[2:3], off
	global_load_dword v14, v[8:9], off offset:-2048
	v_lshl_add_u64 v[2:3], v[2:3], 0, s[16:17]
	global_load_dword v12, v[2:3], off
	global_load_dword v15, v[8:9], off offset:-4096
	v_lshl_add_u64 v[2:3], v[2:3], 0, s[16:17]
	v_add_u32_e32 v4, -1536, v4
	v_cmp_ne_u32_e32 vcc, 0, v7
	v_ashrrev_i32_e32 v8, 6, v7
	v_lshl_add_u32 v8, v8, 3, v6
	s_waitcnt vmcnt(5)
	v_mul_f32_e32 v208, v1, v10
	ds_write_b64 v8, v[208:209]
	v_add_u32_e32 v5, 0x2000, v7
	v_ashrrev_i32_e32 v5, 6, v5
	v_lshlrev_b32_e32 v5, 3, v5
	v_add3_u32 v5, v6, v5, s23
	s_waitcnt vmcnt(4)
	v_mul_f32_e32 v208, v1, v13
	v_cndmask_b32_e32 v208, 0, v208, vcc
	ds_write_b64 v5, v[208:209]
	v_add_u32_e32 v6, 0x1000, v6
	v_add_u32_e32 v7, 0x200, v7
	v_cmp_ne_u32_e32 vcc, 0, v7
	v_ashrrev_i32_e32 v8, 6, v7
	v_lshl_add_u32 v8, v8, 3, v6
	s_waitcnt vmcnt(3)
	v_mul_f32_e32 v208, v1, v11
	ds_write_b64 v8, v[208:209]
	v_add_u32_e32 v5, 0x2000, v7
	v_ashrrev_i32_e32 v5, 6, v5
	v_lshlrev_b32_e32 v5, 3, v5
	v_add3_u32 v5, v6, v5, s23
	s_waitcnt vmcnt(2)
	v_mul_f32_e32 v208, v1, v14
	v_cndmask_b32_e32 v208, 0, v208, vcc
	ds_write_b64 v5, v[208:209]
	v_add_u32_e32 v6, 0x1000, v6
	v_add_u32_e32 v7, 0x200, v7
	v_cmp_ne_u32_e32 vcc, 0, v7
	v_ashrrev_i32_e32 v8, 6, v7
	v_lshl_add_u32 v8, v8, 3, v6
	s_waitcnt vmcnt(1)
	v_mul_f32_e32 v208, v1, v12
	ds_write_b64 v8, v[208:209]
	v_add_u32_e32 v5, 0x2000, v7
	v_ashrrev_i32_e32 v5, 6, v5
	v_lshlrev_b32_e32 v5, 3, v5
	v_add3_u32 v5, v6, v5, s23
	s_waitcnt vmcnt(0)
	v_mul_f32_e32 v208, v1, v15
	v_cndmask_b32_e32 v208, 0, v208, vcc
	ds_write_b64 v5, v[208:209]
	v_add_u32_e32 v6, 0x1000, v6
	v_add_u32_e32 v7, 0x200, v7
	v_mov_b32_e32 v5, v209
	v_lshl_add_u64 v[8:9], v[4:5], 2, s[4:5]
	global_load_dword v10, v[2:3], off
	global_load_dword v13, v[8:9], off
	v_lshl_add_u64 v[2:3], v[2:3], 0, s[16:17]
	global_load_dword v11, v[2:3], off
	global_load_dword v14, v[8:9], off offset:-2048
	v_lshl_add_u64 v[2:3], v[2:3], 0, s[16:17]
	global_load_dword v12, v[2:3], off
	global_load_dword v15, v[8:9], off offset:-4096
	v_lshl_add_u64 v[2:3], v[2:3], 0, s[16:17]
	v_add_u32_e32 v4, -1536, v4
	v_cmp_ne_u32_e32 vcc, 0, v7
	v_ashrrev_i32_e32 v8, 6, v7
	v_lshl_add_u32 v8, v8, 3, v6
	s_waitcnt vmcnt(5)
	v_mul_f32_e32 v208, v1, v10
	ds_write_b64 v8, v[208:209]
	v_add_u32_e32 v5, 0x2000, v7
	v_ashrrev_i32_e32 v5, 6, v5
	v_lshlrev_b32_e32 v5, 3, v5
	v_add3_u32 v5, v6, v5, s23
	s_waitcnt vmcnt(4)
	v_mul_f32_e32 v208, v1, v13
	v_cndmask_b32_e32 v208, 0, v208, vcc
	ds_write_b64 v5, v[208:209]
	v_add_u32_e32 v6, 0x1000, v6
	v_add_u32_e32 v7, 0x200, v7
	v_cmp_ne_u32_e32 vcc, 0, v7
	v_ashrrev_i32_e32 v8, 6, v7
	v_lshl_add_u32 v8, v8, 3, v6
	s_waitcnt vmcnt(3)
	v_mul_f32_e32 v208, v1, v11
	ds_write_b64 v8, v[208:209]
	v_add_u32_e32 v5, 0x2000, v7
	v_ashrrev_i32_e32 v5, 6, v5
	v_lshlrev_b32_e32 v5, 3, v5
	v_add3_u32 v5, v6, v5, s23
	s_waitcnt vmcnt(2)
	v_mul_f32_e32 v208, v1, v14
	v_cndmask_b32_e32 v208, 0, v208, vcc
	ds_write_b64 v5, v[208:209]
	v_add_u32_e32 v6, 0x1000, v6
	v_add_u32_e32 v7, 0x200, v7
	v_cmp_ne_u32_e32 vcc, 0, v7
	v_ashrrev_i32_e32 v8, 6, v7
	v_lshl_add_u32 v8, v8, 3, v6
	s_waitcnt vmcnt(1)
	v_mul_f32_e32 v208, v1, v12
	ds_write_b64 v8, v[208:209]
	v_add_u32_e32 v5, 0x2000, v7
	v_ashrrev_i32_e32 v5, 6, v5
	v_lshlrev_b32_e32 v5, 3, v5
	v_add3_u32 v5, v6, v5, s23
	s_waitcnt vmcnt(0)
	v_mul_f32_e32 v208, v1, v15
	v_cndmask_b32_e32 v208, 0, v208, vcc
	ds_write_b64 v5, v[208:209]
	v_add_u32_e32 v6, 0x1000, v6
	v_add_u32_e32 v7, 0x200, v7
	v_mov_b32_e32 v5, v209
	v_lshl_add_u64 v[8:9], v[4:5], 2, s[4:5]
	global_load_dword v10, v[2:3], off
	global_load_dword v13, v[8:9], off
	v_lshl_add_u64 v[2:3], v[2:3], 0, s[16:17]
	v_add_u32_e32 v4, -512, v4
	v_cmp_ne_u32_e32 vcc, 0, v7
	v_ashrrev_i32_e32 v8, 6, v7
	v_lshl_add_u32 v8, v8, 3, v6
	s_waitcnt vmcnt(1)
	v_mul_f32_e32 v208, v1, v10
	ds_write_b64 v8, v[208:209]
	v_add_u32_e32 v5, 0x2000, v7
	v_ashrrev_i32_e32 v5, 6, v5
	v_lshlrev_b32_e32 v5, 3, v5
	v_add3_u32 v5, v6, v5, s23
	s_waitcnt vmcnt(0)
	v_mul_f32_e32 v208, v1, v13
	v_cndmask_b32_e32 v208, 0, v208, vcc
	ds_write_b64 v5, v[208:209]
	v_add_u32_e32 v6, 0x1000, v6
	v_add_u32_e32 v7, 0x200, v7
